# dilated attention epilogue: O stores and previous-group O loads widened from 8x dwordx2 to 4x dwordx4 via v_permlane32_swap pairs (bit-identical)
# baseline (speedup 1.0000x reference)
.LBB0_305:
	s_cmp_eq_u64 s[4:5], 0
	s_cbranch_scc1 .Ldil_nopf
	v_ashrrev_i32_e32 v239, 31, v126
	v_mov_b32_e32 v238, v126
	v_lshlrev_b64 v[234:235], 6, v[122:123]
	v_lshl_add_u64 v[234:235], s[62:63], 0, v[234:235]
	v_lshl_add_u64 v[234:235], v[238:239], 2, v[234:235]
	global_load_dword v240, v[234:235], off
	v_lshlrev_b64 v[230:231], 11, v[122:123]
	v_lshl_add_u64 v[230:231], s[36:37], 0, v[230:231]
	v_lshl_add_u64 v[230:231], v[124:125], 1, v[230:231]
	v_lshlrev_b32_e32 v232, 2, v129
	v_mov_b32_e32 v233, 0
	v_lshl_add_u64 v[230:231], v[230:231], 0, v[232:233]
	global_load_dwordx4 v[214:217], v[230:231], off
	global_load_dwordx4 v[218:221], v[230:231], off offset:32
	global_load_dwordx4 v[222:225], v[230:231], off offset:64
	global_load_dwordx4 v[226:229], v[230:231], off offset:96

.LBB0_309:
	s_or_b64 exec, exec, s[0:1]
	v_lshlrev_b64 v[38:39], 11, v[122:123]
	v_lshl_add_u64 v[38:39], s[36:37], 0, v[38:39]
	v_lshl_add_u64 v[38:39], v[124:125], 1, v[38:39]
	v_lshlrev_b32_e32 v0, 2, v129
	v_lshl_add_u64 v[38:39], v[38:39], 0, v[0:1]
	v_mov_b32_e32 v37, v36
	s_cmp_eq_u64 s[4:5], 0
	s_cbranch_scc1 .Ldil_st_first
	v_permlane32_swap_b32_e32 v214, v216
	v_permlane32_swap_b32_e32 v215, v217
	v_permlane32_swap_b32_e32 v218, v220
	v_permlane32_swap_b32_e32 v219, v221
	v_permlane32_swap_b32_e32 v222, v224
	v_permlane32_swap_b32_e32 v223, v225
	v_permlane32_swap_b32_e32 v226, v228
	v_permlane32_swap_b32_e32 v227, v229
	v_pk_mul_f32 v[2:3], v[2:3], v[36:37]
	v_pk_mul_f32 v[4:5], v[4:5], v[36:37]
	v_and_b32_e32 v57, 0xffff0000, v214
	v_lshlrev_b32_e32 v56, 16, v214
	v_pk_fma_f32 v[2:3], v[34:35], v[56:57], v[2:3] op_sel_hi:[0,1,1]
	v_and_b32_e32 v59, 0xffff0000, v215
	v_lshlrev_b32_e32 v58, 16, v215
	v_pk_fma_f32 v[4:5], v[34:35], v[58:59], v[4:5] op_sel_hi:[0,1,1]
	v_pk_mul_f32 v[6:7], v[6:7], v[36:37]
	v_pk_mul_f32 v[8:9], v[8:9], v[36:37]
	v_and_b32_e32 v57, 0xffff0000, v216
	v_lshlrev_b32_e32 v56, 16, v216
	v_pk_fma_f32 v[6:7], v[34:35], v[56:57], v[6:7] op_sel_hi:[0,1,1]
	v_and_b32_e32 v59, 0xffff0000, v217
	v_lshlrev_b32_e32 v58, 16, v217
	v_pk_fma_f32 v[8:9], v[34:35], v[58:59], v[8:9] op_sel_hi:[0,1,1]
	v_pk_mul_f32 v[10:11], v[10:11], v[36:37]
	v_pk_mul_f32 v[12:13], v[12:13], v[36:37]
	v_and_b32_e32 v57, 0xffff0000, v218
	v_lshlrev_b32_e32 v56, 16, v218
	v_pk_fma_f32 v[10:11], v[34:35], v[56:57], v[10:11] op_sel_hi:[0,1,1]
	v_and_b32_e32 v59, 0xffff0000, v219
	v_lshlrev_b32_e32 v58, 16, v219
	v_pk_fma_f32 v[12:13], v[34:35], v[58:59], v[12:13] op_sel_hi:[0,1,1]
	v_pk_mul_f32 v[14:15], v[14:15], v[36:37]
	v_pk_mul_f32 v[16:17], v[16:17], v[36:37]
	v_and_b32_e32 v57, 0xffff0000, v220
	v_lshlrev_b32_e32 v56, 16, v220
	v_pk_fma_f32 v[14:15], v[34:35], v[56:57], v[14:15] op_sel_hi:[0,1,1]
	v_and_b32_e32 v59, 0xffff0000, v221
	v_lshlrev_b32_e32 v58, 16, v221
	v_pk_fma_f32 v[16:17], v[34:35], v[58:59], v[16:17] op_sel_hi:[0,1,1]
	v_pk_mul_f32 v[18:19], v[18:19], v[36:37]
	v_pk_mul_f32 v[20:21], v[20:21], v[36:37]
	v_and_b32_e32 v57, 0xffff0000, v222
	v_lshlrev_b32_e32 v56, 16, v222
	v_pk_fma_f32 v[18:19], v[34:35], v[56:57], v[18:19] op_sel_hi:[0,1,1]
	v_and_b32_e32 v59, 0xffff0000, v223
	v_lshlrev_b32_e32 v58, 16, v223
	v_pk_fma_f32 v[20:21], v[34:35], v[58:59], v[20:21] op_sel_hi:[0,1,1]
	v_pk_mul_f32 v[22:23], v[22:23], v[36:37]
	v_pk_mul_f32 v[24:25], v[24:25], v[36:37]
	v_and_b32_e32 v57, 0xffff0000, v224
	v_lshlrev_b32_e32 v56, 16, v224
	v_pk_fma_f32 v[22:23], v[34:35], v[56:57], v[22:23] op_sel_hi:[0,1,1]
	v_and_b32_e32 v59, 0xffff0000, v225
	v_lshlrev_b32_e32 v58, 16, v225
	v_pk_fma_f32 v[24:25], v[34:35], v[58:59], v[24:25] op_sel_hi:[0,1,1]
	v_pk_mul_f32 v[26:27], v[26:27], v[36:37]
	v_pk_mul_f32 v[28:29], v[28:29], v[36:37]
	v_and_b32_e32 v57, 0xffff0000, v226
	v_lshlrev_b32_e32 v56, 16, v226
	v_pk_fma_f32 v[26:27], v[34:35], v[56:57], v[26:27] op_sel_hi:[0,1,1]
	v_and_b32_e32 v59, 0xffff0000, v227
	v_lshlrev_b32_e32 v58, 16, v227
	v_pk_fma_f32 v[28:29], v[34:35], v[58:59], v[28:29] op_sel_hi:[0,1,1]
	v_pk_mul_f32 v[30:31], v[30:31], v[36:37]
	v_pk_mul_f32 v[32:33], v[32:33], v[36:37]
	v_and_b32_e32 v57, 0xffff0000, v228
	v_lshlrev_b32_e32 v56, 16, v228
	v_pk_fma_f32 v[30:31], v[34:35], v[56:57], v[30:31] op_sel_hi:[0,1,1]
	v_and_b32_e32 v59, 0xffff0000, v229
	v_lshlrev_b32_e32 v58, 16, v229
	v_pk_fma_f32 v[32:33], v[34:35], v[58:59], v[32:33] op_sel_hi:[0,1,1]
	s_branch .Ldil_st_cvt
.Ldil_st_first:
	v_pk_mul_f32 v[2:3], v[2:3], v[36:37]
	v_pk_mul_f32 v[4:5], v[4:5], v[36:37]
	v_pk_mul_f32 v[6:7], v[6:7], v[36:37]
	v_pk_mul_f32 v[8:9], v[8:9], v[36:37]
	v_pk_mul_f32 v[10:11], v[10:11], v[36:37]
	v_pk_mul_f32 v[12:13], v[12:13], v[36:37]
	v_pk_mul_f32 v[14:15], v[14:15], v[36:37]
	v_pk_mul_f32 v[16:17], v[16:17], v[36:37]
	v_pk_mul_f32 v[18:19], v[18:19], v[36:37]
	v_pk_mul_f32 v[20:21], v[20:21], v[36:37]
	v_pk_mul_f32 v[22:23], v[22:23], v[36:37]
	v_pk_mul_f32 v[24:25], v[24:25], v[36:37]
	v_pk_mul_f32 v[26:27], v[26:27], v[36:37]
	v_pk_mul_f32 v[28:29], v[28:29], v[36:37]
	v_pk_mul_f32 v[30:31], v[30:31], v[36:37]
	v_pk_mul_f32 v[32:33], v[32:33], v[36:37]
.Ldil_st_cvt:
	v_cvt_pk_bf16_f32 v40, v2, v3
	v_cvt_pk_bf16_f32 v41, v4, v5
	v_cvt_pk_bf16_f32 v42, v6, v7
	v_cvt_pk_bf16_f32 v43, v8, v9
	s_nop 1
	v_permlane32_swap_b32_e32 v40, v42
	v_permlane32_swap_b32_e32 v41, v43
	global_store_dwordx4 v[38:39], v[40:43], off
	v_cvt_pk_bf16_f32 v44, v10, v11
	v_cvt_pk_bf16_f32 v45, v12, v13
	v_cvt_pk_bf16_f32 v46, v14, v15
	v_cvt_pk_bf16_f32 v47, v16, v17
	s_nop 1
	v_permlane32_swap_b32_e32 v44, v46
	v_permlane32_swap_b32_e32 v45, v47
	global_store_dwordx4 v[38:39], v[44:47], off offset:32
	v_cvt_pk_bf16_f32 v48, v18, v19
	v_cvt_pk_bf16_f32 v49, v20, v21
	v_cvt_pk_bf16_f32 v50, v22, v23
	v_cvt_pk_bf16_f32 v51, v24, v25
	s_nop 1
	v_permlane32_swap_b32_e32 v48, v50
	v_permlane32_swap_b32_e32 v49, v51
	global_store_dwordx4 v[38:39], v[48:51], off offset:64
	v_cvt_pk_bf16_f32 v52, v26, v27
	v_cvt_pk_bf16_f32 v53, v28, v29
	v_cvt_pk_bf16_f32 v54, v30, v31
	v_cvt_pk_bf16_f32 v55, v32, v33
	s_nop 1
	v_permlane32_swap_b32_e32 v52, v54
	v_permlane32_swap_b32_e32 v53, v55
	global_store_dwordx4 v[38:39], v[52:55], off offset:96
	s_add_i32 s14, s14, 1
	s_cmp_eq_u32 s14, s54
	s_cselect_b64 s[0:1], -1, 0
	s_branch .LBB0_285
